# M_RES epilogue (PH, PK residual add) software-pipelined: 12 row-chunk loads in flight, counted vmcnt waits, no store drains
# speedup vs baseline: 1.0011x; 1.0011x over previous
.LBB0_32:
	s_or_b64 exec, exec, s[2:3]
	v_lshlrev_b64 v[158:159], 2, v[154:155]
	v_lshl_add_u64 v[154:155], v[162:163], 0, v[158:159]
	v_lshl_add_u64 v[160:161], s[6:7], 0, v[160:161]
	v_lshl_add_u64 v[160:161], v[160:161], 0, v[158:159]
	global_load_dwordx4 v[168:171], v[154:155], off
	global_load_dwordx4 v[172:175], v[154:155], off offset:64
	global_load_dwordx4 v[176:179], v[154:155], off offset:512
	global_load_dwordx4 v[180:183], v[154:155], off offset:576
	s_mov_b64 s[2:3], 0x10000
	v_lshl_add_u64 v[162:163], v[154:155], 0, s[2:3]
	global_load_dwordx4 v[184:187], v[162:163], off
	global_load_dwordx4 v[188:191], v[162:163], off offset:64
	global_load_dwordx4 v[196:199], v[162:163], off offset:512
	global_load_dwordx4 v[200:203], v[162:163], off offset:576
	s_mov_b64 s[2:3], 0x20000
	v_lshl_add_u64 v[156:157], v[154:155], 0, s[2:3]
	global_load_dwordx4 v[206:209], v[156:157], off
	global_load_dwordx4 v[210:213], v[156:157], off offset:64
	global_load_dwordx4 v[214:217], v[156:157], off offset:512
	global_load_dwordx4 v[218:221], v[156:157], off offset:576
	s_mov_b32 s49, s5
	s_mov_b32 s54, s18
	s_mov_b64 s[14:15], s[10:11]
	s_waitcnt vmcnt(8)
	v_pk_fma_f32 v[142:143], v[142:143], v[102:103], v[168:169]
	v_pk_fma_f32 v[144:145], v[144:145], v[104:105], v[170:171]
	v_pk_fma_f32 v[138:139], v[138:139], v[98:99], v[172:173]
	v_pk_fma_f32 v[140:141], v[140:141], v[100:101], v[174:175]
	v_pk_fma_f32 v[134:135], v[134:135], v[94:95], v[176:177]
	v_pk_fma_f32 v[136:137], v[136:137], v[96:97], v[178:179]
	v_pk_fma_f32 v[130:131], v[130:131], v[90:91], v[180:181]
	v_pk_fma_f32 v[132:133], v[132:133], v[92:93], v[182:183]
	global_store_dwordx4 v[160:161], v[142:145], off
	global_store_dwordx4 v[160:161], v[138:141], off offset:64
	global_store_dwordx4 v[160:161], v[134:137], off offset:512
	global_store_dwordx4 v[160:161], v[130:133], off offset:576
	s_mov_b64 s[2:3], 0x30000
	v_lshl_add_u64 v[162:163], v[154:155], 0, s[2:3]
	global_load_dwordx4 v[168:171], v[162:163], off
	global_load_dwordx4 v[172:175], v[162:163], off offset:64
	global_load_dwordx4 v[176:179], v[162:163], off offset:512
	global_load_dwordx4 v[180:183], v[162:163], off offset:576
	s_mov_b64 s[2:3], 0x80000
	v_lshl_add_u64 v[156:157], v[154:155], 0, s[2:3]
	global_load_dwordx4 v[142:145], v[156:157], off
	global_load_dwordx4 v[138:141], v[156:157], off offset:64
	global_load_dwordx4 v[134:137], v[156:157], off offset:512
	global_load_dwordx4 v[130:133], v[156:157], off offset:576
	s_waitcnt vmcnt(16)
	v_pk_fma_f32 v[126:127], v[126:127], v[102:103], v[184:185]
	v_pk_fma_f32 v[128:129], v[128:129], v[104:105], v[186:187]
	v_pk_fma_f32 v[122:123], v[122:123], v[98:99], v[188:189]
	v_pk_fma_f32 v[124:125], v[124:125], v[100:101], v[190:191]
	v_pk_fma_f32 v[118:119], v[118:119], v[94:95], v[196:197]
	v_pk_fma_f32 v[120:121], v[120:121], v[96:97], v[198:199]
	v_pk_fma_f32 v[114:115], v[114:115], v[90:91], v[200:201]
	v_pk_fma_f32 v[116:117], v[116:117], v[92:93], v[202:203]
	s_mov_b64 s[2:3], 0x10000
	v_lshl_add_u64 v[192:193], v[160:161], 0, s[2:3]
	global_store_dwordx4 v[192:193], v[126:129], off
	global_store_dwordx4 v[192:193], v[122:125], off offset:64
	global_store_dwordx4 v[192:193], v[118:121], off offset:512
	global_store_dwordx4 v[192:193], v[114:117], off offset:576
	s_mov_b64 s[2:3], 0x90000
	v_lshl_add_u64 v[162:163], v[154:155], 0, s[2:3]
	global_load_dwordx4 v[184:187], v[162:163], off
	global_load_dwordx4 v[188:191], v[162:163], off offset:64
	global_load_dwordx4 v[196:199], v[162:163], off offset:512
	global_load_dwordx4 v[200:203], v[162:163], off offset:576
	s_mov_b64 s[2:3], 0xa0000
	v_lshl_add_u64 v[156:157], v[154:155], 0, s[2:3]
	global_load_dwordx4 v[126:129], v[156:157], off
	global_load_dwordx4 v[122:125], v[156:157], off offset:64
	global_load_dwordx4 v[118:121], v[156:157], off offset:512
	global_load_dwordx4 v[114:117], v[156:157], off offset:576
	s_waitcnt vmcnt(24)
	v_pk_fma_f32 v[110:111], v[110:111], v[102:103], v[206:207]
	v_pk_fma_f32 v[112:113], v[112:113], v[104:105], v[208:209]
	v_pk_fma_f32 v[106:107], v[106:107], v[98:99], v[210:211]
	v_pk_fma_f32 v[108:109], v[108:109], v[100:101], v[212:213]
	v_pk_fma_f32 v[86:87], v[86:87], v[94:95], v[214:215]
	v_pk_fma_f32 v[88:89], v[88:89], v[96:97], v[216:217]
	v_pk_fma_f32 v[82:83], v[82:83], v[90:91], v[218:219]
	v_pk_fma_f32 v[84:85], v[84:85], v[92:93], v[220:221]
	s_mov_b64 s[2:3], 0x20000
	v_lshl_add_u64 v[222:223], v[160:161], 0, s[2:3]
	global_store_dwordx4 v[222:223], v[110:113], off
	global_store_dwordx4 v[222:223], v[106:109], off offset:64
	global_store_dwordx4 v[222:223], v[86:89], off offset:512
	global_store_dwordx4 v[222:223], v[82:85], off offset:576
	s_mov_b64 s[2:3], 0xb0000
	v_lshl_add_u64 v[162:163], v[154:155], 0, s[2:3]
	global_load_dwordx4 v[206:209], v[162:163], off
	global_load_dwordx4 v[210:213], v[162:163], off offset:64
	global_load_dwordx4 v[214:217], v[162:163], off offset:512
	global_load_dwordx4 v[218:221], v[162:163], off offset:576
	s_waitcnt vmcnt(24)
	v_pk_fma_f32 v[78:79], v[78:79], v[102:103], v[168:169]
	v_pk_fma_f32 v[80:81], v[80:81], v[104:105], v[170:171]
	v_pk_fma_f32 v[74:75], v[74:75], v[98:99], v[172:173]
	v_pk_fma_f32 v[76:77], v[76:77], v[100:101], v[174:175]
	v_pk_fma_f32 v[70:71], v[70:71], v[94:95], v[176:177]
	v_pk_fma_f32 v[72:73], v[72:73], v[96:97], v[178:179]
	v_pk_fma_f32 v[66:67], v[66:67], v[90:91], v[180:181]
	v_pk_fma_f32 v[68:69], v[68:69], v[92:93], v[182:183]
	s_mov_b64 s[2:3], 0x30000
	v_lshl_add_u64 v[192:193], v[160:161], 0, s[2:3]
	global_store_dwordx4 v[192:193], v[78:81], off
	global_store_dwordx4 v[192:193], v[74:77], off offset:64
	global_store_dwordx4 v[192:193], v[70:73], off offset:512
	global_store_dwordx4 v[192:193], v[66:69], off offset:576
	s_waitcnt vmcnt(24)
	v_pk_fma_f32 v[62:63], v[62:63], v[102:103], v[142:143]
	v_pk_fma_f32 v[64:65], v[64:65], v[104:105], v[144:145]
	v_pk_fma_f32 v[58:59], v[58:59], v[98:99], v[138:139]
	v_pk_fma_f32 v[60:61], v[60:61], v[100:101], v[140:141]
	v_pk_fma_f32 v[46:47], v[46:47], v[94:95], v[134:135]
	v_pk_fma_f32 v[48:49], v[48:49], v[96:97], v[136:137]
	v_pk_fma_f32 v[42:43], v[42:43], v[90:91], v[130:131]
	v_pk_fma_f32 v[44:45], v[44:45], v[92:93], v[132:133]
	s_mov_b64 s[2:3], 0x80000
	v_lshl_add_u64 v[222:223], v[160:161], 0, s[2:3]
	global_store_dwordx4 v[222:223], v[62:65], off
	global_store_dwordx4 v[222:223], v[58:61], off offset:64
	global_store_dwordx4 v[222:223], v[46:49], off offset:512
	global_store_dwordx4 v[222:223], v[42:45], off offset:576
	s_waitcnt vmcnt(20)
	v_pk_fma_f32 v[54:55], v[54:55], v[102:103], v[184:185]
	v_pk_fma_f32 v[56:57], v[56:57], v[104:105], v[186:187]
	v_pk_fma_f32 v[50:51], v[50:51], v[98:99], v[188:189]
	v_pk_fma_f32 v[52:53], v[52:53], v[100:101], v[190:191]
	v_pk_fma_f32 v[38:39], v[38:39], v[94:95], v[196:197]
	v_pk_fma_f32 v[40:41], v[40:41], v[96:97], v[198:199]
	v_pk_fma_f32 v[34:35], v[34:35], v[90:91], v[200:201]
	v_pk_fma_f32 v[36:37], v[36:37], v[92:93], v[202:203]
	s_mov_b64 s[2:3], 0x90000
	v_lshl_add_u64 v[192:193], v[160:161], 0, s[2:3]
	global_store_dwordx4 v[192:193], v[54:57], off
	global_store_dwordx4 v[192:193], v[50:53], off offset:64
	global_store_dwordx4 v[192:193], v[38:41], off offset:512
	global_store_dwordx4 v[192:193], v[34:37], off offset:576
	s_waitcnt vmcnt(20)
	v_pk_fma_f32 v[30:31], v[30:31], v[102:103], v[126:127]
	v_pk_fma_f32 v[32:33], v[32:33], v[104:105], v[128:129]
	v_pk_fma_f32 v[26:27], v[26:27], v[98:99], v[122:123]
	v_pk_fma_f32 v[28:29], v[28:29], v[100:101], v[124:125]
	v_pk_fma_f32 v[14:15], v[14:15], v[94:95], v[118:119]
	v_pk_fma_f32 v[16:17], v[16:17], v[96:97], v[120:121]
	v_pk_fma_f32 v[10:11], v[10:11], v[90:91], v[114:115]
	v_pk_fma_f32 v[12:13], v[12:13], v[92:93], v[116:117]
	s_mov_b64 s[2:3], 0xa0000
	v_lshl_add_u64 v[222:223], v[160:161], 0, s[2:3]
	global_store_dwordx4 v[222:223], v[30:33], off
	global_store_dwordx4 v[222:223], v[26:29], off offset:64
	global_store_dwordx4 v[222:223], v[14:17], off offset:512
	global_store_dwordx4 v[222:223], v[10:13], off offset:576
	s_waitcnt vmcnt(16)
	v_pk_fma_f32 v[22:23], v[22:23], v[102:103], v[206:207]
	v_pk_fma_f32 v[24:25], v[24:25], v[104:105], v[208:209]
	v_pk_fma_f32 v[18:19], v[18:19], v[98:99], v[210:211]
	v_pk_fma_f32 v[20:21], v[20:21], v[100:101], v[212:213]
	v_pk_fma_f32 v[6:7], v[6:7], v[94:95], v[214:215]
	v_pk_fma_f32 v[8:9], v[8:9], v[96:97], v[216:217]
	v_pk_fma_f32 v[2:3], v[2:3], v[90:91], v[218:219]
	v_pk_fma_f32 v[4:5], v[4:5], v[92:93], v[220:221]
	s_mov_b64 s[2:3], 0xb0000
	v_lshl_add_u64 v[192:193], v[160:161], 0, s[2:3]
	global_store_dwordx4 v[192:193], v[22:25], off
	global_store_dwordx4 v[192:193], v[18:21], off offset:64
	global_store_dwordx4 v[192:193], v[6:9], off offset:512
	global_store_dwordx4 v[192:193], v[2:5], off offset:576
	s_and_b64 vcc, exec, s[36:37]
	s_mov_b64 s[12:13], s[0:1]
	s_cbranch_vccnz .LBB0_45

.LBB0_132:
	s_or_b64 exec, exec, s[2:3]
	v_lshlrev_b64 v[158:159], 2, v[154:155]
	v_lshl_add_u64 v[154:155], v[162:163], 0, v[158:159]
	v_readlane_b32 s2, v249, 8
	v_readlane_b32 s3, v249, 9
	s_nop 0
	v_lshl_add_u64 v[160:161], s[2:3], 0, v[160:161]
	v_lshl_add_u64 v[160:161], v[160:161], 0, v[158:159]
	global_load_dwordx4 v[168:171], v[154:155], off
	global_load_dwordx4 v[172:175], v[154:155], off offset:64
	global_load_dwordx4 v[176:179], v[154:155], off offset:512
	global_load_dwordx4 v[180:183], v[154:155], off offset:576
	s_mov_b64 s[2:3], 0x10000
	v_lshl_add_u64 v[162:163], v[154:155], 0, s[2:3]
	global_load_dwordx4 v[184:187], v[162:163], off
	global_load_dwordx4 v[188:191], v[162:163], off offset:64
	global_load_dwordx4 v[196:199], v[162:163], off offset:512
	global_load_dwordx4 v[200:203], v[162:163], off offset:576
	s_mov_b64 s[2:3], 0x20000
	v_lshl_add_u64 v[156:157], v[154:155], 0, s[2:3]
	global_load_dwordx4 v[206:209], v[156:157], off
	global_load_dwordx4 v[210:213], v[156:157], off offset:64
	global_load_dwordx4 v[214:217], v[156:157], off offset:512
	global_load_dwordx4 v[218:221], v[156:157], off offset:576
	s_mov_b32 s49, s10
	s_mov_b32 s54, s12
	s_mov_b64 s[38:39], s[16:17]
	s_waitcnt vmcnt(8)
	v_pk_fma_f32 v[142:143], v[142:143], v[102:103], v[168:169]
	v_pk_fma_f32 v[144:145], v[144:145], v[104:105], v[170:171]
	v_pk_fma_f32 v[138:139], v[138:139], v[98:99], v[172:173]
	v_pk_fma_f32 v[140:141], v[140:141], v[100:101], v[174:175]
	v_pk_fma_f32 v[134:135], v[134:135], v[94:95], v[176:177]
	v_pk_fma_f32 v[136:137], v[136:137], v[96:97], v[178:179]
	v_pk_fma_f32 v[130:131], v[130:131], v[90:91], v[180:181]
	v_pk_fma_f32 v[132:133], v[132:133], v[92:93], v[182:183]
	global_store_dwordx4 v[160:161], v[142:145], off
	global_store_dwordx4 v[160:161], v[138:141], off offset:64
	global_store_dwordx4 v[160:161], v[134:137], off offset:512
	global_store_dwordx4 v[160:161], v[130:133], off offset:576
	s_mov_b64 s[2:3], 0x30000
	v_lshl_add_u64 v[162:163], v[154:155], 0, s[2:3]
	global_load_dwordx4 v[168:171], v[162:163], off
	global_load_dwordx4 v[172:175], v[162:163], off offset:64
	global_load_dwordx4 v[176:179], v[162:163], off offset:512
	global_load_dwordx4 v[180:183], v[162:163], off offset:576
	s_mov_b64 s[2:3], 0x80000
	v_lshl_add_u64 v[156:157], v[154:155], 0, s[2:3]
	global_load_dwordx4 v[142:145], v[156:157], off
	global_load_dwordx4 v[138:141], v[156:157], off offset:64
	global_load_dwordx4 v[134:137], v[156:157], off offset:512
	global_load_dwordx4 v[130:133], v[156:157], off offset:576
	s_waitcnt vmcnt(16)
	v_pk_fma_f32 v[126:127], v[126:127], v[102:103], v[184:185]
	v_pk_fma_f32 v[128:129], v[128:129], v[104:105], v[186:187]
	v_pk_fma_f32 v[122:123], v[122:123], v[98:99], v[188:189]
	v_pk_fma_f32 v[124:125], v[124:125], v[100:101], v[190:191]
	v_pk_fma_f32 v[118:119], v[118:119], v[94:95], v[196:197]
	v_pk_fma_f32 v[120:121], v[120:121], v[96:97], v[198:199]
	v_pk_fma_f32 v[114:115], v[114:115], v[90:91], v[200:201]
	v_pk_fma_f32 v[116:117], v[116:117], v[92:93], v[202:203]
	s_mov_b64 s[2:3], 0x10000
	v_lshl_add_u64 v[192:193], v[160:161], 0, s[2:3]
	global_store_dwordx4 v[192:193], v[126:129], off
	global_store_dwordx4 v[192:193], v[122:125], off offset:64
	global_store_dwordx4 v[192:193], v[118:121], off offset:512
	global_store_dwordx4 v[192:193], v[114:117], off offset:576
	s_mov_b64 s[2:3], 0x90000
	v_lshl_add_u64 v[162:163], v[154:155], 0, s[2:3]
	global_load_dwordx4 v[184:187], v[162:163], off
	global_load_dwordx4 v[188:191], v[162:163], off offset:64
	global_load_dwordx4 v[196:199], v[162:163], off offset:512
	global_load_dwordx4 v[200:203], v[162:163], off offset:576
	s_mov_b64 s[2:3], 0xa0000
	v_lshl_add_u64 v[156:157], v[154:155], 0, s[2:3]
	global_load_dwordx4 v[126:129], v[156:157], off
	global_load_dwordx4 v[122:125], v[156:157], off offset:64
	global_load_dwordx4 v[118:121], v[156:157], off offset:512
	global_load_dwordx4 v[114:117], v[156:157], off offset:576
	s_waitcnt vmcnt(24)
	v_pk_fma_f32 v[110:111], v[110:111], v[102:103], v[206:207]
	v_pk_fma_f32 v[112:113], v[112:113], v[104:105], v[208:209]
	v_pk_fma_f32 v[106:107], v[106:107], v[98:99], v[210:211]
	v_pk_fma_f32 v[108:109], v[108:109], v[100:101], v[212:213]
	v_pk_fma_f32 v[86:87], v[86:87], v[94:95], v[214:215]
	v_pk_fma_f32 v[88:89], v[88:89], v[96:97], v[216:217]
	v_pk_fma_f32 v[82:83], v[82:83], v[90:91], v[218:219]
	v_pk_fma_f32 v[84:85], v[84:85], v[92:93], v[220:221]
	s_mov_b64 s[2:3], 0x20000
	v_lshl_add_u64 v[222:223], v[160:161], 0, s[2:3]
	global_store_dwordx4 v[222:223], v[110:113], off
	global_store_dwordx4 v[222:223], v[106:109], off offset:64
	global_store_dwordx4 v[222:223], v[86:89], off offset:512
	global_store_dwordx4 v[222:223], v[82:85], off offset:576
	s_mov_b64 s[2:3], 0xb0000
	v_lshl_add_u64 v[162:163], v[154:155], 0, s[2:3]
	global_load_dwordx4 v[206:209], v[162:163], off
	global_load_dwordx4 v[210:213], v[162:163], off offset:64
	global_load_dwordx4 v[214:217], v[162:163], off offset:512
	global_load_dwordx4 v[218:221], v[162:163], off offset:576
	s_waitcnt vmcnt(24)
	v_pk_fma_f32 v[78:79], v[78:79], v[102:103], v[168:169]
	v_pk_fma_f32 v[80:81], v[80:81], v[104:105], v[170:171]
	v_pk_fma_f32 v[74:75], v[74:75], v[98:99], v[172:173]
	v_pk_fma_f32 v[76:77], v[76:77], v[100:101], v[174:175]
	v_pk_fma_f32 v[70:71], v[70:71], v[94:95], v[176:177]
	v_pk_fma_f32 v[72:73], v[72:73], v[96:97], v[178:179]
	v_pk_fma_f32 v[66:67], v[66:67], v[90:91], v[180:181]
	v_pk_fma_f32 v[68:69], v[68:69], v[92:93], v[182:183]
	s_mov_b64 s[2:3], 0x30000
	v_lshl_add_u64 v[192:193], v[160:161], 0, s[2:3]
	global_store_dwordx4 v[192:193], v[78:81], off
	global_store_dwordx4 v[192:193], v[74:77], off offset:64
	global_store_dwordx4 v[192:193], v[70:73], off offset:512
	global_store_dwordx4 v[192:193], v[66:69], off offset:576
	s_waitcnt vmcnt(24)
	v_pk_fma_f32 v[62:63], v[62:63], v[102:103], v[142:143]
	v_pk_fma_f32 v[64:65], v[64:65], v[104:105], v[144:145]
	v_pk_fma_f32 v[58:59], v[58:59], v[98:99], v[138:139]
	v_pk_fma_f32 v[60:61], v[60:61], v[100:101], v[140:141]
	v_pk_fma_f32 v[46:47], v[46:47], v[94:95], v[134:135]
	v_pk_fma_f32 v[48:49], v[48:49], v[96:97], v[136:137]
	v_pk_fma_f32 v[42:43], v[42:43], v[90:91], v[130:131]
	v_pk_fma_f32 v[44:45], v[44:45], v[92:93], v[132:133]
	s_mov_b64 s[2:3], 0x80000
	v_lshl_add_u64 v[222:223], v[160:161], 0, s[2:3]
	global_store_dwordx4 v[222:223], v[62:65], off
	global_store_dwordx4 v[222:223], v[58:61], off offset:64
	global_store_dwordx4 v[222:223], v[46:49], off offset:512
	global_store_dwordx4 v[222:223], v[42:45], off offset:576
	s_waitcnt vmcnt(20)
	v_pk_fma_f32 v[54:55], v[54:55], v[102:103], v[184:185]
	v_pk_fma_f32 v[56:57], v[56:57], v[104:105], v[186:187]
	v_pk_fma_f32 v[50:51], v[50:51], v[98:99], v[188:189]
	v_pk_fma_f32 v[52:53], v[52:53], v[100:101], v[190:191]
	v_pk_fma_f32 v[38:39], v[38:39], v[94:95], v[196:197]
	v_pk_fma_f32 v[40:41], v[40:41], v[96:97], v[198:199]
	v_pk_fma_f32 v[34:35], v[34:35], v[90:91], v[200:201]
	v_pk_fma_f32 v[36:37], v[36:37], v[92:93], v[202:203]
	s_mov_b64 s[2:3], 0x90000
	v_lshl_add_u64 v[192:193], v[160:161], 0, s[2:3]
	global_store_dwordx4 v[192:193], v[54:57], off
	global_store_dwordx4 v[192:193], v[50:53], off offset:64
	global_store_dwordx4 v[192:193], v[38:41], off offset:512
	global_store_dwordx4 v[192:193], v[34:37], off offset:576
	s_waitcnt vmcnt(20)
	v_pk_fma_f32 v[30:31], v[30:31], v[102:103], v[126:127]
	v_pk_fma_f32 v[32:33], v[32:33], v[104:105], v[128:129]
	v_pk_fma_f32 v[26:27], v[26:27], v[98:99], v[122:123]
	v_pk_fma_f32 v[28:29], v[28:29], v[100:101], v[124:125]
	v_pk_fma_f32 v[14:15], v[14:15], v[94:95], v[118:119]
	v_pk_fma_f32 v[16:17], v[16:17], v[96:97], v[120:121]
	v_pk_fma_f32 v[10:11], v[10:11], v[90:91], v[114:115]
	v_pk_fma_f32 v[12:13], v[12:13], v[92:93], v[116:117]
	s_mov_b64 s[2:3], 0xa0000
	v_lshl_add_u64 v[222:223], v[160:161], 0, s[2:3]
	global_store_dwordx4 v[222:223], v[30:33], off
	global_store_dwordx4 v[222:223], v[26:29], off offset:64
	global_store_dwordx4 v[222:223], v[14:17], off offset:512
	global_store_dwordx4 v[222:223], v[10:13], off offset:576
	s_waitcnt vmcnt(16)
	v_pk_fma_f32 v[22:23], v[22:23], v[102:103], v[206:207]
	v_pk_fma_f32 v[24:25], v[24:25], v[104:105], v[208:209]
	v_pk_fma_f32 v[18:19], v[18:19], v[98:99], v[210:211]
	v_pk_fma_f32 v[20:21], v[20:21], v[100:101], v[212:213]
	v_pk_fma_f32 v[6:7], v[6:7], v[94:95], v[214:215]
	v_pk_fma_f32 v[8:9], v[8:9], v[96:97], v[216:217]
	v_pk_fma_f32 v[2:3], v[2:3], v[90:91], v[218:219]
	v_pk_fma_f32 v[4:5], v[4:5], v[92:93], v[220:221]
	s_mov_b64 s[2:3], 0xb0000
	v_lshl_add_u64 v[192:193], v[160:161], 0, s[2:3]
	global_store_dwordx4 v[192:193], v[22:25], off
	global_store_dwordx4 v[192:193], v[18:21], off offset:64
	global_store_dwordx4 v[192:193], v[6:9], off offset:512
	global_store_dwordx4 v[192:193], v[2:5], off offset:576
	s_and_b64 vcc, exec, s[36:37]
	s_mov_b64 s[18:19], s[14:15]
	s_cbranch_vccnz .LBB0_141
